# attention K/V tile staging by direct HBM->LDS loads (LDS-DMA) into the padded [row][272B] LDS image: 68 lane-linear 1 KiB blocks per tile, per-lane source offsets precomputed once; no VGPR staging, no
# speedup vs baseline: 1.0122x; 1.0068x over previous
; #define LAS __attribute__((address_space(3)))
; __device__ __forceinline__ float fexp2(float x) { return __builtin_amdgcn_exp2f(x); }
;     __device__ __forceinline__ PT() { out = (float*)(__attribute__((address_space(1))) float*)ptab_get(23); ws = (unsigned char*)(__attribute__((address_space(1))) unsigned char*)ptab_get(24); }
; #define PREFETCH(t) do { \
;         _Pragma("unroll") for (int i_ = 0; i_ < 4; ++i_) { const int pid_ = tid + 512 * i_, row_ = pid_ >> 4, c16_ = pid_ & 15; const unsigned go_ = (tokb + (unsigned)((t) * 128 + row_)) * 2048u + (unsigned)(hd * 128 + 8 * c16_); \
;             preK[i_] = *(const u32x4*)(Kb + go_); preV[i_] = *(const u32x4*)(Vb + go_); } \
;     } while (0)
; __device__ __forceinline__ void attn_unit(const PT& p, LAS unsigned char* lds, int tid, int lane, int wave, int b, int hd, int qb, float lam) {
;     unsigned char* ws = p.ws;
;     const bf16* Qb = (const bf16*)(ws + WS_Q); const bf16* Kb = (const bf16*)(ws + WS_K); const bf16* Vb = (const bf16*)(ws + WS_VV); const bf16* Gb = (const bf16*)((unsigned char*)p.out + DO_G);
;     bf16* Ob = (bf16*)(ws + WS_O);
;     const int r32 = lane & 31, h = lane >> 5, mp = wave >> 2, wq = wave & 3;
;     const int qw0 = qb * 128 + 32 * wq, q = qw0 + r32; const unsigned tokq = (unsigned)(b * SEQ + q), tokb = (unsigned)(b * SEQ);
;     const float slope2 = fexp2(-0.5f * (float)(hd + 1)) * LOG2E;
;     bf16x8 qf[4];
; #pragma unroll
;     for (int ds = 0; ds < 4; ++ds) qf[ds] = ld_frag16(Qb + (tokq * 2048u + (unsigned)(hd * 128 + mp * 64 + 16 * ds + 8 * h)));
;     float mrun = -INFINITY, lsum = 0.f;
;     f32x16 oT[4];
; #pragma unroll
;     for (int db = 0; db < 4; ++db)
; #pragma unroll
;         for (int i = 0; i < 16; ++i) oT[db][i] = 0.f;
;     const int ntiles = qb + 1;
;     u32x4 preV[4], preK[4];
;     ...
;     PREFETCH(0);
;     const LAS unsigned char* kbase0 = lds + A_KOFF + r32 * AK_PITCH + (mp * 64 + 8 * h) * 2;
;     const LAS unsigned char* vbase0 = lds + A_VOFF + (4 * h + ((lane & 15) >> 2)) * AV_PITCH + ((lane >> 4) & 1) * 32 + (lane & 3) * 8;
; __device__ __forceinline__ void phase_attn(const PT& p, LAS unsigned char* lds, int tid, int lane, int wave) {
;     const float s1 = wave_sum(p.in[16][lane] * p.in[17][lane]), s2 = wave_sum(p.in[18][lane] * p.in[19][lane]);
;     const float lam = __expf(s1) - __expf(s2) + LAMBDA_INIT;
.LBB0_1069:
	s_or_b64 exec, exec, s[0:1]
	s_waitcnt lgkmcnt(0)
	v_mov_b32_e32 v0, 0x23eb8
	s_barrier
	ds_read_b64 v[2:3], v0
	v_mov_b32_e32 v0, 0x23ec0
	ds_read_b64 v[6:7], v0
	v_mov_b32_e32 v0, v196
	v_mov_b32_e32 v1, 0x23e80
	ds_read_b64 v[4:5], v1
	v_mov_b32_e32 v8, 0x23e90
	v_mov_b32_e32 v10, 0x23e98
	ds_read_b64 v[8:9], v8
	ds_read_b64 v[10:11], v10
	s_waitcnt lgkmcnt(2)
	v_readfirstlane_b32 s0, v4
	v_mov_b32_e32 v4, 0x23e88
	v_readfirstlane_b32 s1, v5
	ds_read_b64 v[4:5], v4
	v_and_b32_e32 v198, 63, v0
	v_lshlrev_b32_e32 v1, 2, v198
	s_waitcnt lgkmcnt(2)
	v_readfirstlane_b32 s5, v9
	v_readfirstlane_b32 s4, v8
	s_waitcnt lgkmcnt(0)
	v_readfirstlane_b32 s3, v5
	v_readfirstlane_b32 s2, v4
	v_readfirstlane_b32 s7, v11
	v_readfirstlane_b32 s6, v10
	global_load_dword v4, v1, s[0:1]
	s_nop 1
	global_load_dword v5, v1, s[2:3]
	global_load_dword v8, v1, s[4:5]
	global_load_dword v9, v1, s[6:7]
	v_mbcnt_hi_u32_b32 v1, -1, v182
	v_and_b32_e32 v10, 64, v1
	v_xor_b32_e32 v11, 1, v1
	v_add_u32_e32 v10, 64, v10
	v_cmp_lt_i32_e32 vcc, v11, v10
	v_xor_b32_e32 v12, 2, v1
	v_xor_b32_e32 v13, 4, v1
	v_cndmask_b32_e32 v11, v1, v11, vcc
	v_lshlrev_b32_e32 v11, 2, v11
	v_cmp_lt_i32_e32 vcc, v12, v10
	v_xor_b32_e32 v14, 8, v1
	v_xor_b32_e32 v15, 16, v1
	v_cndmask_b32_e32 v12, v1, v12, vcc
	v_lshlrev_b32_e32 v12, 2, v12
	v_cmp_lt_i32_e32 vcc, v13, v10
	v_xor_b32_e32 v16, 32, v1
	v_readfirstlane_b32 s2, v2
	v_cndmask_b32_e32 v13, v1, v13, vcc
	v_cmp_lt_i32_e32 vcc, v14, v10
	v_readfirstlane_b32 s3, v3
	v_readfirstlane_b32 s0, v7
	v_readfirstlane_b32 s1, v6
	s_cmpk_gt_i32 s90, 0x3ff
	v_readfirstlane_b32 s4, v0
	s_waitcnt vmcnt(2)
	v_mul_f32_e32 v17, v4, v5
	ds_bpermute_b32 v17, v11, v17
	s_waitcnt vmcnt(0)
	v_mul_f32_e32 v18, v8, v9
	ds_bpermute_b32 v11, v11, v18
	s_waitcnt lgkmcnt(1)
	v_fmac_f32_e32 v17, v4, v5
	ds_bpermute_b32 v4, v12, v17
	s_waitcnt lgkmcnt(1)
	v_fmac_f32_e32 v11, v8, v9
	ds_bpermute_b32 v5, v12, v11
	v_lshlrev_b32_e32 v9, 2, v13
	v_cndmask_b32_e32 v8, v1, v14, vcc
	s_waitcnt lgkmcnt(1)
	v_add_f32_e32 v4, v17, v4
	v_lshlrev_b32_e32 v8, 2, v8
	s_waitcnt lgkmcnt(0)
	v_add_f32_e32 v5, v11, v5
	ds_bpermute_b32 v11, v9, v4
	ds_bpermute_b32 v9, v9, v5
	v_cmp_lt_i32_e32 vcc, v15, v10
	s_waitcnt lgkmcnt(1)
	v_add_f32_e32 v4, v4, v11
	s_waitcnt lgkmcnt(0)
	v_add_f32_e32 v5, v5, v9
	ds_bpermute_b32 v9, v8, v4
	ds_bpermute_b32 v8, v8, v5
	v_cndmask_b32_e32 v12, v1, v15, vcc
	v_lshlrev_b32_e32 v179, 2, v12
	v_cmp_lt_i32_e32 vcc, v16, v10
	s_waitcnt lgkmcnt(1)
	v_add_f32_e32 v4, v4, v9
	s_waitcnt lgkmcnt(0)
	v_add_f32_e32 v5, v5, v8
	ds_bpermute_b32 v8, v179, v4
	ds_bpermute_b32 v9, v179, v5
	v_cndmask_b32_e32 v1, v1, v16, vcc
	v_lshlrev_b32_e32 v197, 2, v1
	s_waitcnt lgkmcnt(1)
	v_add_f32_e32 v1, v4, v8
	s_waitcnt lgkmcnt(0)
	v_add_f32_e32 v2, v5, v9
	ds_bpermute_b32 v3, v197, v1
	ds_bpermute_b32 v4, v197, v2
	s_cbranch_scc1 .LBB0_1111
	s_waitcnt lgkmcnt(1)
	v_add_f32_e32 v1, v1, v3
	s_waitcnt lgkmcnt(0)
	v_add_f32_e32 v2, v2, v4
	v_mul_f32_e32 v1, 0x3fb8aa3b, v1
	v_mul_f32_e32 v2, 0x3fb8aa3b, v2
	v_exp_f32_e32 v1, v1
	v_exp_f32_e32 v2, v2
	s_ashr_i32 s36, s4, 6
	s_add_u32 s40, s1, 0x6900000
	s_addc_u32 s41, s0, 0
	v_sub_f32_e32 v1, v1, v2
	s_add_u32 s42, s1, 0x1a900000
	v_lshrrev_b32_e32 v2, 5, v198
	s_addc_u32 s43, s0, 0
	s_ashr_i32 s37, s4, 8
	v_lshlrev_b32_e32 v3, 3, v2
	s_and_b32 s38, s36, 3
	v_lshl_or_b32 v200, s37, 6, v3
	v_lshlrev_b32_e32 v3, 3, v0
	s_add_u32 s44, s1, 0xe900000
	v_and_b32_e32 v201, 0x78, v3
	v_add_u32_e32 v3, 0x200, v0
	s_addc_u32 s45, s0, 0
	v_lshrrev_b32_e32 v203, 4, v3
	v_add_u32_e32 v3, 0x400, v0
	v_add_f32_e32 v199, 0x3eb60549, v1
	v_and_b32_e32 v1, 31, v0
	s_add_u32 s46, s1, 0xa900000
	v_lshrrev_b32_e32 v202, 4, v0
	v_lshrrev_b32_e32 v204, 4, v3
	v_add_u32_e32 v3, 0x600, v0
	v_lshrrev_b32_e32 v4, 2, v0
	v_lshlrev_b32_e32 v0, 4, v0
	s_addc_u32 s47, s0, 0
	s_lshl_b32 s1, s37, 7
	v_lshlrev_b32_e32 v178, 2, v2
	v_and_b32_e32 v0, 0xf0, v0
	v_lshrrev_b32_e32 v205, 4, v3
	s_movk_i32 s0, 0x110
	v_mul_u32_u24_e32 v3, 0x110, v1
	s_add_i32 s1, s1, 0
	v_and_b32_e32 v4, 3, v4
	v_lshl_or_b32 v4, v4, 2, v2
	v_lshlrev_b32_e32 v5, 1, v198
	v_lshlrev_b32_e32 v6, 3, v198
	v_add_u32_e32 v206, 0, v0
	v_lshlrev_b32_e32 v0, 4, v2
	v_and_b32_e32 v5, 32, v5
	v_and_b32_e32 v6, 24, v6
	v_add3_u32 v211, s1, v3, v0
	v_mad_u32_u24 v0, v4, s0, 0
	v_add3_u32 v212, v0, v5, v6
	v_or_b32_e32 v0, 2, v178
	v_cmp_gt_u32_e64 s[6:7], v0, v1
	v_or_b32_e32 v0, 3, v178
	v_cmp_gt_u32_e64 s[8:9], v0, v1
	v_or_b32_e32 v0, 9, v178
	v_cmp_gt_u32_e64 s[12:13], v0, v1
	v_or_b32_e32 v0, 10, v178
	v_cmp_gt_u32_e64 s[14:15], v0, v1
	v_or_b32_e32 v0, 11, v178
	v_cmp_gt_u32_e64 s[16:17], v0, v1
	v_or_b32_e32 v0, 17, v178
	v_cmp_gt_u32_e64 s[20:21], v0, v1
	v_or_b32_e32 v0, 18, v178
	s_cmp_lg_u32 s38, 0
	v_cmp_gt_u32_e64 s[22:23], v0, v1
	v_or_b32_e32 v0, 19, v178
	s_cselect_b64 s[48:49], -1, 0
	s_cmp_eq_u32 s38, 0
	v_cmp_gt_u32_e64 s[24:25], v0, v1
	v_or_b32_e32 v0, 25, v178
	s_cselect_b64 s[50:51], -1, 0
	v_cmp_gt_u32_e64 s[28:29], v0, v1
	v_or_b32_e32 v0, 26, v178
	s_cmp_eq_u32 s38, 1
	v_cmp_gt_u32_e64 s[30:31], v0, v1
	v_or_b32_e32 v0, 27, v178
	s_cselect_b64 s[52:53], -1, 0
	s_cmp_eq_u32 s38, 2
	v_cmp_gt_u32_e64 s[34:35], v0, v1
	v_sub_u32_e64 v0, s38, 1 clamp
	s_cselect_b64 s[54:55], -1, 0
	s_cmp_eq_u32 s38, 3
	v_readfirstlane_b32 s33, v0
	s_cselect_b64 s[56:57], -1, 0
	s_lshl_b32 s39, s38, 14
	v_lshl_or_b32 v0, v205, 11, v201
	v_writelane_b32 v249, s70, 41
	s_add_i32 s86, s39, 0
	v_add_u32_e32 v229, 0x40000, v0
	v_lshl_or_b32 v0, v204, 11, v201
	v_writelane_b32 v249, s71, 42
	s_cmp_eq_u32 s37, 1
	v_add_u32_e32 v230, 0x40000, v0
	v_lshl_or_b32 v0, v203, 11, v201
; #define LAS __attribute__((address_space(3)))
; #define PREFETCH(t) do { \
;         _Pragma("unroll") for (int i_ = 0; i_ < 4; ++i_) { const int pid_ = tid + 512 * i_, row_ = pid_ >> 4, c16_ = pid_ & 15; const unsigned go_ = (tokb + (unsigned)((t) * 128 + row_)) * 2048u + (unsigned)(hd * 128 + 8 * c16_); \
;             preK[i_] = *(const u32x4*)(Kb + go_); preV[i_] = *(const u32x4*)(Vb + go_); } \
;     } while (0)
; __device__ __forceinline__ void attn_unit(const PT& p, LAS unsigned char* lds, int tid, int lane, int wave, int b, int hd, int qb, float lam) {
;     ...
;     PREFETCH(0);
;     const LAS unsigned char* kbase0 = lds + A_KOFF + r32 * AK_PITCH + (mp * 64 + 8 * h) * 2;
;     const LAS unsigned char* vbase0 = lds + A_VOFF + (4 * h + ((lane & 15) >> 2)) * AV_PITCH + ((lane >> 4) & 1) * 32 + (lane & 3) * 8;
	v_or_b32_e32 v213, 8, v178
	v_or_b32_e32 v214, 16, v178
	v_or_b32_e32 v215, 24, v178
	s_cselect_b64 s[58:59], -1, 0
	s_cmp_lt_u32 s36, 4
	v_readlane_b32 s36, v249, 0
	v_add_u32_e32 v231, 0x40000, v0
	v_lshl_or_b32 v0, v202, 11, v201
	s_mov_b32 s62, 2.0
	s_mov_b32 s64, 0x41000000
	s_mov_b32 s66, 0x41200000
	s_mov_b32 s68, 0x41800000
	s_mov_b32 s70, 0x41900000
	s_mov_b32 s72, 0x41c00000
	s_mov_b32 s74, 0x41d00000
	v_mul_lo_u32 v207, v202, s0
	v_mul_lo_u32 v208, v203, s0
	v_mul_lo_u32 v209, v204, s0
	v_mul_lo_u32 v210, v205, s0
	v_cmp_gt_u32_e64 s[0:1], v178, v1
	v_cmp_lt_u32_e64 s[4:5], v178, v1
	v_cmp_gt_u32_e64 s[10:11], v213, v1
	v_cmp_gt_u32_e64 s[18:19], v214, v1
	v_cmp_gt_u32_e64 s[26:27], v215, v1
	s_cselect_b64 s[60:61], -1, 0
	v_mov_b32_e32 v51, 0
	v_or_b32_e32 v216, 32, v178
	v_or_b32_e32 v217, 40, v178
	v_or_b32_e32 v218, 48, v178
	v_or_b32_e32 v219, 56, v178
	v_or_b32_e32 v220, 64, v178
	v_or_b32_e32 v221, 0x48, v178
	v_or_b32_e32 v222, 0x50, v178
	v_or_b32_e32 v223, 0x58, v178
	v_or_b32_e32 v224, 0x60, v178
	v_or_b32_e32 v225, 0x68, v178
	v_or_b32_e32 v226, 0x70, v178
	v_or_b32_e32 v227, 0x78, v178
	v_lshl_or_b32 v228, s38, 5, v1
	s_lshl_b32 s38, s90, 4
	s_lshl_b32 s36, s36, 4
	v_add_u32_e32 v232, 0x40000, v0
	s_mov_b32 s63, 0x40400000
	s_mov_b32 s65, 0x41100000
	s_mov_b32 s67, 0x41300000
	s_mov_b32 s69, 0x41880000
	s_mov_b32 s71, 0x41980000
	s_mov_b32 s73, 0x41c80000
	s_mov_b32 s75, 0x41d80000
	s_mov_b32 s89, 0xff800000
	v_mov_b32_e32 v233, 0x23ea0
	v_mov_b32_e32 v234, 0x3727c5ac
	v_mov_b32_e32 v16, 0xff800000
	v_readlane_b32 s37, v249, 1
	v_writelane_b32 v249, s36, 39
	v_lshrrev_b32_e32 v0, 6, v196
	v_add_u32_e32 v1, 0, v0
	v_cmp_gt_u32_e32 vcc, 34, v1
	v_subrev_u32_e32 v2, 34, v1
	s_nop 1
	v_cndmask_b32_e32 v1, v2, v1, vcc
	v_lshl_add_u32 v3, v1, 6, v198
	v_mul_u32_u24_e32 v4, 0xf10, v3
	v_lshrrev_b32_e32 v4, 16, v4
	v_mul_u32_u24_e32 v5, 17, v4
	v_sub_u32_e32 v5, v3, v5
	v_min_u32_e32 v5, 15, v5
	v_and_b32_e32 v6, 3, v4
	v_bfe_u32 v7, v4, 2, 2
	v_lshl_or_b32 v6, v6, 2, v7
	v_and_b32_e32 v7, 0xfffffff0, v4
	v_or_b32_e32 v6, v7, v6
	v_cndmask_b32_e32 v4, v6, v4, vcc
	v_lshlrev_b32_e32 v4, 12, v4
	v_lshl_add_u32 v229, v5, 4, v4
	v_add_u32_e32 v1, 8, v0
	v_cmp_gt_u32_e32 vcc, 34, v1
	v_subrev_u32_e32 v2, 34, v1
	s_nop 1
	v_cndmask_b32_e32 v1, v2, v1, vcc
	v_lshl_add_u32 v3, v1, 6, v198
	v_mul_u32_u24_e32 v4, 0xf10, v3
	v_lshrrev_b32_e32 v4, 16, v4
	v_mul_u32_u24_e32 v5, 17, v4
	v_sub_u32_e32 v5, v3, v5
	v_min_u32_e32 v5, 15, v5
	v_and_b32_e32 v6, 3, v4
	v_bfe_u32 v7, v4, 2, 2
	v_lshl_or_b32 v6, v6, 2, v7
	v_and_b32_e32 v7, 0xfffffff0, v4
	v_or_b32_e32 v6, v7, v6
	v_cndmask_b32_e32 v4, v6, v4, vcc
	v_lshlrev_b32_e32 v4, 12, v4
	v_lshl_add_u32 v230, v5, 4, v4
	v_add_u32_e32 v1, 16, v0
	v_cmp_gt_u32_e32 vcc, 34, v1
	v_subrev_u32_e32 v2, 34, v1
	s_nop 1
	v_cndmask_b32_e32 v1, v2, v1, vcc
	v_lshl_add_u32 v3, v1, 6, v198
	v_mul_u32_u24_e32 v4, 0xf10, v3
	v_lshrrev_b32_e32 v4, 16, v4
	v_mul_u32_u24_e32 v5, 17, v4
	v_sub_u32_e32 v5, v3, v5
	v_min_u32_e32 v5, 15, v5
	v_and_b32_e32 v6, 3, v4
	v_bfe_u32 v7, v4, 2, 2
	v_lshl_or_b32 v6, v6, 2, v7
	v_and_b32_e32 v7, 0xfffffff0, v4
	v_or_b32_e32 v6, v7, v6
	v_cndmask_b32_e32 v4, v6, v4, vcc
	v_lshlrev_b32_e32 v4, 12, v4
	v_lshl_add_u32 v231, v5, 4, v4
	v_add_u32_e32 v1, 24, v0
	v_cmp_gt_u32_e32 vcc, 34, v1
	v_subrev_u32_e32 v2, 34, v1
	s_nop 1
	v_cndmask_b32_e32 v1, v2, v1, vcc
	v_lshl_add_u32 v3, v1, 6, v198
	v_mul_u32_u24_e32 v4, 0xf10, v3
	v_lshrrev_b32_e32 v4, 16, v4
	v_mul_u32_u24_e32 v5, 17, v4
	v_sub_u32_e32 v5, v3, v5
	v_min_u32_e32 v5, 15, v5
	v_and_b32_e32 v6, 3, v4
	v_bfe_u32 v7, v4, 2, 2
	v_lshl_or_b32 v6, v6, 2, v7
	v_and_b32_e32 v7, 0xfffffff0, v4
	v_or_b32_e32 v6, v7, v6
	v_cndmask_b32_e32 v4, v6, v4, vcc
	v_lshlrev_b32_e32 v4, 12, v4
	v_lshl_add_u32 v232, v5, 4, v4
	v_add_u32_e32 v1, 32, v0
	v_cmp_gt_u32_e32 vcc, 34, v1
	v_subrev_u32_e32 v2, 34, v1
	s_nop 1
	v_cndmask_b32_e32 v1, v2, v1, vcc
	v_lshl_add_u32 v3, v1, 6, v198
	v_mul_u32_u24_e32 v4, 0xf10, v3
	v_lshrrev_b32_e32 v4, 16, v4
	v_mul_u32_u24_e32 v5, 17, v4
	v_sub_u32_e32 v5, v3, v5
	v_min_u32_e32 v5, 15, v5
	v_and_b32_e32 v6, 3, v4
	v_bfe_u32 v7, v4, 2, 2
	v_lshl_or_b32 v6, v6, 2, v7
	v_and_b32_e32 v7, 0xfffffff0, v4
	v_or_b32_e32 v6, v7, v6
	v_cndmask_b32_e32 v4, v6, v4, vcc
	v_lshlrev_b32_e32 v4, 12, v4
	v_lshl_add_u32 v235, v5, 4, v4
	v_add_u32_e32 v1, 40, v0
	v_cmp_gt_u32_e32 vcc, 34, v1
	v_subrev_u32_e32 v2, 34, v1
	s_nop 1
	v_cndmask_b32_e32 v1, v2, v1, vcc
	v_lshl_add_u32 v3, v1, 6, v198
	v_mul_u32_u24_e32 v4, 0xf10, v3
	v_lshrrev_b32_e32 v4, 16, v4
	v_mul_u32_u24_e32 v5, 17, v4
	v_sub_u32_e32 v5, v3, v5
	v_min_u32_e32 v5, 15, v5
	v_and_b32_e32 v6, 3, v4
	v_bfe_u32 v7, v4, 2, 2
	v_lshl_or_b32 v6, v6, 2, v7
	v_and_b32_e32 v7, 0xfffffff0, v4
	v_or_b32_e32 v6, v7, v6
	v_cndmask_b32_e32 v4, v6, v4, vcc
	v_lshlrev_b32_e32 v4, 12, v4
	v_lshl_add_u32 v236, v5, 4, v4
	v_add_u32_e32 v1, 48, v0
	v_cmp_gt_u32_e32 vcc, 34, v1
	v_subrev_u32_e32 v2, 34, v1
	s_nop 1
	v_cndmask_b32_e32 v1, v2, v1, vcc
	v_lshl_add_u32 v3, v1, 6, v198
	v_mul_u32_u24_e32 v4, 0xf10, v3
	v_lshrrev_b32_e32 v4, 16, v4
	v_mul_u32_u24_e32 v5, 17, v4
	v_sub_u32_e32 v5, v3, v5
	v_min_u32_e32 v5, 15, v5
	v_and_b32_e32 v6, 3, v4
	v_bfe_u32 v7, v4, 2, 2
	v_lshl_or_b32 v6, v6, 2, v7
	v_and_b32_e32 v7, 0xfffffff0, v4
	v_or_b32_e32 v6, v7, v6
	v_cndmask_b32_e32 v4, v6, v4, vcc
	v_lshlrev_b32_e32 v4, 12, v4
	v_lshl_add_u32 v237, v5, 4, v4
	v_add_u32_e32 v1, 56, v0
	v_cmp_gt_u32_e32 vcc, 34, v1
	v_subrev_u32_e32 v2, 34, v1
	s_nop 1
	v_cndmask_b32_e32 v1, v2, v1, vcc
	v_lshl_add_u32 v3, v1, 6, v198
	v_mul_u32_u24_e32 v4, 0xf10, v3
	v_lshrrev_b32_e32 v4, 16, v4
	v_mul_u32_u24_e32 v5, 17, v4
	v_sub_u32_e32 v5, v3, v5
	v_min_u32_e32 v5, 15, v5
	v_and_b32_e32 v6, 3, v4
	v_bfe_u32 v7, v4, 2, 2
	v_lshl_or_b32 v6, v6, 2, v7
	v_and_b32_e32 v7, 0xfffffff0, v4
	v_or_b32_e32 v6, v7, v6
	v_cndmask_b32_e32 v4, v6, v4, vcc
	v_lshlrev_b32_e32 v4, 12, v4
	v_lshl_add_u32 v238, v5, 4, v4
	v_add_u32_e32 v1, 64, v0
	v_min_u32_e32 v1, 0x43, v1
	v_cmp_gt_u32_e32 vcc, 34, v1
	v_subrev_u32_e32 v2, 34, v1
	s_nop 1
	v_cndmask_b32_e32 v1, v2, v1, vcc
	v_lshl_add_u32 v3, v1, 6, v198
	v_mul_u32_u24_e32 v4, 0xf10, v3
	v_lshrrev_b32_e32 v4, 16, v4
	v_mul_u32_u24_e32 v5, 17, v4
	v_sub_u32_e32 v5, v3, v5
	v_min_u32_e32 v5, 15, v5
	v_and_b32_e32 v6, 3, v4
	v_bfe_u32 v7, v4, 2, 2
	v_lshl_or_b32 v6, v6, 2, v7
	v_and_b32_e32 v7, 0xfffffff0, v4
	v_or_b32_e32 v6, v7, v6
	v_cndmask_b32_e32 v4, v6, v4, vcc
	v_lshlrev_b32_e32 v4, 12, v4
	v_lshl_add_u32 v206, v5, 4, v4
	s_branch .LBB0_1072

; __device__ __forceinline__ float fexp2(float x) { return __builtin_amdgcn_exp2f(x); }
; __device__ __forceinline__ void attn_unit(const PT& p, LAS unsigned char* lds, int tid, int lane, int wave, int b, int hd, int qb, float lam) {
;     ...
;     const int qw0 = qb * 128 + 32 * wq, q = qw0 + r32; const unsigned tokq = (unsigned)(b * SEQ + q), tokb = (unsigned)(b * SEQ);
;     const float slope2 = fexp2(-0.5f * (float)(hd + 1)) * LOG2E;
;     bf16x8 qf[4];
; #pragma unroll
;     for (int ds = 0; ds < 4; ++ds) qf[ds] = ld_frag16(Qb + (tokq * 2048u + (unsigned)(hd * 128 + mp * 64 + 16 * ds + 8 * h)));
; __device__ __forceinline__ void phase_attn(const PT& p, LAS unsigned char* lds, int tid, int lane, int wave) {
;     ...
;     for (int u = blockIdx.x; u < NBATCH * 16 * 8; u += gridDim.x) {
;         const int j = u & 7, hd = (u >> 3) & 15, b = u >> 7;
; #pragma unroll 1
;         for (int k = 0; k < 2; ++k) attn_unit(p, lds, tid, lane, wave, b, hd, k == 0 ? 15 - j : j, lam);
.LBB0_1072:
	s_and_b32 s98, s90, 0xffffffc0
	s_bfe_u32 s99, s90, 0x30003
	s_or_b32 s98, s98, s99
	s_and_b32 s99, s90, 7
	s_lshl_b32 s99, s99, 3
	s_or_b32 s98, s98, s99
	s_lshr_b32 s99, s90, 8
	s_and_b32 s36, s99, 1
	s_mul_i32 s36, s36, 7
	s_lshr_b32 s99, s99, 1
	s_lshl_b32 s99, s99, 3
	s_or_b32 s99, s99, s36
	s_lshl_b32 s36, s98, 15
	s_bfe_u32 s37, s98, 0x40003
	s_xor_b32 s37, s37, s99
	s_and_b32 s36, s36, 0xffc00000
	s_lshl_b32 s91, s37, 7
	s_or_b32 s36, s91, s36
	s_add_i32 s37, s37, 1
	s_lshl_b32 s36, s98, 4
	v_cvt_f32_ubyte0_e32 v0, s37
	s_and_b32 s94, s36, 0xfffff800
	v_mul_f32_e32 v0, -0.5, v0
	v_exp_f32_e32 v2, v0
	v_or_b32_e32 v3, s91, v201
	v_add_u32_e32 v0, s94, v202
	v_lshl_or_b32 v50, v0, 11, v3
	v_lshlrev_b64 v[0:1], 1, v[50:51]
	v_lshl_add_u64 v[180:181], s[46:47], 0, v[0:1]
	v_lshl_add_u64 v[182:183], s[42:43], 0, v[0:1]
	v_add_u32_e32 v0, s94, v203
	v_lshl_or_b32 v50, v0, 11, v3
	v_lshlrev_b64 v[0:1], 1, v[50:51]
	v_lshl_add_u64 v[184:185], s[46:47], 0, v[0:1]
	v_lshl_add_u64 v[186:187], s[42:43], 0, v[0:1]
	v_add_u32_e32 v0, s94, v204
	v_lshl_or_b32 v50, v0, 11, v3
	v_lshlrev_b64 v[0:1], 1, v[50:51]
	v_lshl_add_u64 v[188:189], s[46:47], 0, v[0:1]
	v_lshl_add_u64 v[190:191], s[42:43], 0, v[0:1]
	v_add_u32_e32 v0, s94, v205
	v_lshl_or_b32 v50, v0, 11, v3
	s_and_b32 s92, s98, 7
	v_lshlrev_b64 v[0:1], 1, v[50:51]
	s_xor_b32 s93, s92, 15
	v_add_u32_e32 v239, s91, v200
	v_lshl_add_u64 v[192:193], s[46:47], 0, v[0:1]
	v_lshl_add_u64 v[194:195], s[42:43], 0, v[0:1]
	v_mul_f32_e32 v240, 0x3fb8aa3b, v2
	s_mov_b64 s[36:37], -1
	v_writelane_b32 v249, s38, 37
	s_branch .LBB0_1074

; #define LAS __attribute__((address_space(3)))
; #define PREFETCH(t) do { \
;         _Pragma("unroll") for (int i_ = 0; i_ < 4; ++i_) { const int pid_ = tid + 512 * i_, row_ = pid_ >> 4, c16_ = pid_ & 15; const unsigned go_ = (tokb + (unsigned)((t) * 128 + row_)) * 2048u + (unsigned)(hd * 128 + 8 * c16_); \
;             preK[i_] = *(const u32x4*)(Kb + go_); preV[i_] = *(const u32x4*)(Vb + go_); } \
;     } while (0)
; #define STAGE_WRITE(stg) do { \
;         _Pragma("unroll") for (int i_ = 0; i_ < 4; ++i_) { const int pid_ = tid + 512 * i_, row_ = pid_ >> 4, c16_ = pid_ & 15; \
;             *(LAS u32x4*)(lds + (stg) * A_STAGE + A_KOFF + row_ * AK_PITCH + 16 * c16_) = preK[i_]; *(LAS u32x4*)(lds + (stg) * A_STAGE + A_VOFF + row_ * AV_PITCH + 16 * c16_) = preV[i_]; } \
;     } while (0)
; __device__ __forceinline__ void attn_unit(const PT& p, LAS unsigned char* lds, int tid, int lane, int wave, int b, int hd, int qb, float lam) {
;     ...
;     PREFETCH(0);
;     const LAS unsigned char* kbase0 = lds + A_KOFF + r32 * AK_PITCH + (mp * 64 + 8 * h) * 2;
;     const LAS unsigned char* vbase0 = lds + A_VOFF + (4 * h + ((lane & 15) >> 2)) * AV_PITCH + ((lane >> 4) & 1) * 32 + (lane & 3) * 8;
;     ...
;     __syncthreads();
;     STAGE_WRITE(0);
;     asm volatile("" : "+v"(qf[0]), "+v"(qf[1]), "+v"(qf[2]), "+v"(qf[3]));
;     __syncthreads();
; #pragma unroll 1
;     for (int t = 0; t < ntiles; ++t) {
;         const int stg = t & 1;
;         if (t + 1 < ntiles) PREFETCH(t + 1);
.LBB0_1074:
	s_xor_b64 s[76:77], s[36:37], -1
	s_and_b64 s[36:37], s[36:37], exec
	s_cselect_b32 s95, s93, s92
	v_lshl_or_b32 v8, s95, 7, v228
	v_or_b32_e32 v0, s94, v8
	v_lshlrev_b32_e32 v241, 11, v0
	v_add_u32_e32 v50, v239, v241
	v_lshl_add_u64 v[0:1], v[50:51], 1, s[40:41]
	v_or_b32_e32 v2, 16, v50
	v_mov_b32_e32 v3, v51
	v_or_b32_e32 v4, 32, v50
	v_mov_b32_e32 v5, v51
	v_or_b32_e32 v50, 48, v50
	v_lshl_add_u64 v[2:3], v[2:3], 1, s[40:41]
	v_lshl_add_u64 v[4:5], v[4:5], 1, s[40:41]
	v_lshl_add_u64 v[6:7], v[50:51], 1, s[40:41]
	s_lshl_b32 s96, s95, 18
	global_load_dwordx4 v[130:133], v[0:1], off
	global_load_dwordx4 v[142:145], v[6:7], off
	global_load_dwordx4 v[146:149], v[4:5], off
	global_load_dwordx4 v[150:153], v[2:3], off
	s_barrier
	s_mov_b32 s98, s96
	s_lshl_b32 s99, s94, 11
	s_add_i32 s99, s99, s91
	s_add_i32 s99, s99, s98
	s_lshl_b32 s99, s99, 1
	s_mov_b32 s87, 0
	v_readfirstlane_b32 s100, v196
	s_lshr_b32 s100, s100, 6
	s_cmp_lt_u32 s100, 2
	s_cselect_b32 s36, s46, s42
	s_cselect_b32 s37, s47, s43
	s_add_i32 s101, s100, 64
	s_min_u32 s101, s101, 0x43
	s_lshl_b32 s101, s101, 10
	s_lshl_b32 s100, s100, 10
	s_add_i32 s100, s100, s87
	s_add_i32 s101, s101, s87
	s_mov_b32 m0, s100
	v_add_u32_e32 v1, s99, v229
	global_load_lds_dwordx4 v1, s[46:47]
	s_add_i32 m0, s100, 0x2000
	v_add_u32_e32 v1, s99, v230
	global_load_lds_dwordx4 v1, s[46:47]
	s_add_i32 m0, s100, 0x4000
	v_add_u32_e32 v1, s99, v231
	global_load_lds_dwordx4 v1, s[46:47]
	s_add_i32 m0, s100, 0x6000
	v_add_u32_e32 v1, s99, v232
	global_load_lds_dwordx4 v1, s[46:47]
	s_add_i32 m0, s100, 0x8000
	v_add_u32_e32 v1, s99, v235
	global_load_lds_dwordx4 v1, s[36:37]
	s_add_i32 m0, s100, 0xa000
	v_add_u32_e32 v1, s99, v236
	global_load_lds_dwordx4 v1, s[42:43]
	s_add_i32 m0, s100, 0xc000
	v_add_u32_e32 v1, s99, v237
	global_load_lds_dwordx4 v1, s[42:43]
	s_add_i32 m0, s100, 0xe000
	v_add_u32_e32 v1, s99, v238
	global_load_lds_dwordx4 v1, s[42:43]
	s_mov_b32 m0, s101
	v_add_u32_e32 v1, s99, v206
	global_load_lds_dwordx4 v1, s[42:43]
	v_mov_b32_e32 v64, v51
	v_mov_b32_e32 v65, v51
	s_lshl_b32 s96, s95, 18
	v_mov_b32_e32 v50, v51
	v_mov_b32_e32 v52, v51
	v_mov_b32_e32 v53, v51
	v_mov_b32_e32 v54, v51
	v_mov_b32_e32 v55, v51
	v_mov_b32_e32 v56, v51
	v_mov_b32_e32 v57, v51
	v_mov_b32_e32 v58, v51
	v_mov_b32_e32 v59, v51
	v_mov_b32_e32 v60, v51
	v_mov_b32_e32 v61, v51
	v_mov_b32_e32 v62, v51
	v_mov_b32_e32 v63, v51
	v_mov_b64_e32 v[80:81], v[64:65]
	v_mov_b64_e32 v[96:97], v[64:65]
	v_mov_b64_e32 v[112:113], v[64:65]
	v_mov_b64_e32 v[128:129], v[64:65]
	v_sub_u32_e32 v242, v178, v8
	v_lshl_add_u32 v242, s95, 7, v242
	s_mov_b32 s97, 0xfffc0000
	s_mov_b32 s38, s96
	v_mov_b32_e32 v248, 0xff800000
	v_mov_b32_e32 v243, 0
	v_mov_b64_e32 v[78:79], v[62:63]
	v_mov_b64_e32 v[76:77], v[60:61]
	v_mov_b64_e32 v[74:75], v[58:59]
	v_mov_b64_e32 v[72:73], v[56:57]
	v_mov_b64_e32 v[70:71], v[54:55]
	v_mov_b64_e32 v[68:69], v[52:53]
	v_mov_b64_e32 v[66:67], v[50:51]
	v_mov_b64_e32 v[94:95], v[62:63]
	v_mov_b64_e32 v[92:93], v[60:61]
	v_mov_b64_e32 v[90:91], v[58:59]
	v_mov_b64_e32 v[88:89], v[56:57]
	v_mov_b64_e32 v[86:87], v[54:55]
	v_mov_b64_e32 v[84:85], v[52:53]
	v_mov_b64_e32 v[82:83], v[50:51]
	v_mov_b64_e32 v[110:111], v[62:63]
	v_mov_b64_e32 v[108:109], v[60:61]
	v_mov_b64_e32 v[106:107], v[58:59]
	v_mov_b64_e32 v[104:105], v[56:57]
	v_mov_b64_e32 v[102:103], v[54:55]
	v_mov_b64_e32 v[100:101], v[52:53]
	v_mov_b64_e32 v[98:99], v[50:51]
	v_mov_b64_e32 v[126:127], v[62:63]
	v_mov_b64_e32 v[124:125], v[60:61]
	v_mov_b64_e32 v[122:123], v[58:59]
	v_mov_b64_e32 v[120:121], v[56:57]
	v_mov_b64_e32 v[118:119], v[54:55]
	v_mov_b64_e32 v[116:117], v[52:53]
	v_mov_b64_e32 v[114:115], v[50:51]
	s_mov_b32 s39, 0
	s_waitcnt vmcnt(0)
	s_waitcnt lgkmcnt(0)
	s_barrier
	s_branch .LBB0_1076
.LBB0_1075:
	s_sub_i32 s38, s38, 0x40000
	s_add_i32 s39, s39, 1
	s_cmp_eq_u32 s97, s38
	v_add_u32_e32 v242, 0xffffff80, v242
	s_waitcnt vmcnt(0) lgkmcnt(0)
	s_barrier
	s_cbranch_scc1 .LBB0_1106
.LBB0_1076:
	s_cmp_lt_u32 s39, s95
	s_cselect_b64 s[78:79], -1, 0
	s_cmp_ge_u32 s39, s95
	s_cbranch_scc1 .LBB0_1078
	s_sub_i32 s98, s38, 0x40000
	s_lshl_b32 s99, s94, 11
	s_add_i32 s99, s99, s91
	s_add_i32 s99, s99, s98
	s_lshl_b32 s99, s99, 1
	s_and_b32 s87, s39, 1
	s_xor_b32 s87, s87, 1
	s_mul_i32 s87, s87, 0x11000
	v_readfirstlane_b32 s100, v196
	s_lshr_b32 s100, s100, 6
	s_cmp_lt_u32 s100, 2
	s_cselect_b32 s36, s46, s42
	s_cselect_b32 s37, s47, s43
	s_add_i32 s101, s100, 64
	s_min_u32 s101, s101, 0x43
	s_lshl_b32 s101, s101, 10
	s_lshl_b32 s100, s100, 10
	s_add_i32 s100, s100, s87
	s_add_i32 s101, s101, s87
	s_mov_b32 m0, s100
	v_add_u32_e32 v1, s99, v229
	global_load_lds_dwordx4 v1, s[46:47]
	s_add_i32 m0, s100, 0x2000
	v_add_u32_e32 v1, s99, v230
	global_load_lds_dwordx4 v1, s[46:47]
	s_add_i32 m0, s100, 0x4000
	v_add_u32_e32 v1, s99, v231
	global_load_lds_dwordx4 v1, s[46:47]
	s_add_i32 m0, s100, 0x6000
	v_add_u32_e32 v1, s99, v232
	global_load_lds_dwordx4 v1, s[46:47]
	s_add_i32 m0, s100, 0x8000
	v_add_u32_e32 v1, s99, v235
	global_load_lds_dwordx4 v1, s[36:37]
	s_add_i32 m0, s100, 0xa000
	v_add_u32_e32 v1, s99, v236
	global_load_lds_dwordx4 v1, s[42:43]
	s_add_i32 m0, s100, 0xc000
	v_add_u32_e32 v1, s99, v237
	global_load_lds_dwordx4 v1, s[42:43]
	s_add_i32 m0, s100, 0xe000
	v_add_u32_e32 v1, s99, v238
	global_load_lds_dwordx4 v1, s[42:43]
	s_mov_b32 m0, s101
	v_add_u32_e32 v1, s99, v206
	global_load_lds_dwordx4 v1, s[42:43]

; #define STAGE_WRITE(stg) do { \
;         _Pragma("unroll") for (int i_ = 0; i_ < 4; ++i_) { const int pid_ = tid + 512 * i_, row_ = pid_ >> 4, c16_ = pid_ & 15; \
;             *(LAS u32x4*)(lds + (stg) * A_STAGE + A_KOFF + row_ * AK_PITCH + 16 * c16_) = preK[i_]; *(LAS u32x4*)(lds + (stg) * A_STAGE + A_VOFF + row_ * AV_PITCH + 16 * c16_) = preV[i_]; } \
;     } while (0)
; __device__ __forceinline__ void attn_unit(const PT& p, LAS unsigned char* lds, int tid, int lane, int wave, int b, int hd, int qb, float lam) {
;     ...
;         if (t + 1 < ntiles) STAGE_WRITE(stg ^ 1);
;         __syncthreads();
.LBB0_1104:
	s_branch .LBB0_1075
